# adds hand-scheduled P7 epilogue (8 partial loads at once, 2 batched bpermute rounds, in-place relu^2, nt stores)
# baseline (speedup 1.0000x reference)
.LBB0_956:
	v_lshl_add_u32 v130, s37, 8, v172
	v_lshlrev_b32_e32 v132, 6, v130
	v_mov_b32_e32 v133, 0
	v_lshl_add_u64 v[132:133], v[148:149], 0, v[132:133]
	global_load_dwordx4 v[212:215], v[132:133], off
	global_load_dwordx4 v[216:219], v[132:133], off offset:1024
	global_load_dwordx4 v[220:223], v[132:133], off offset:2048
	global_load_dwordx4 v[224:227], v[132:133], off offset:3072
	v_add_co_u32_e32 v132, vcc, 0x2000, v132
	s_nop 1
	v_addc_co_u32_e32 v133, vcc, 0, v133, vcc
	global_load_dwordx4 v[228:231], v[132:133], off
	global_load_dwordx4 v[232:235], v[132:133], off offset:1024
	global_load_dwordx4 v[236:239], v[132:133], off offset:2048
	global_load_dwordx4 v[240:243], v[132:133], off offset:3072
	s_lshl_b32 s2, s26, 9
	v_readlane_b32 s3, v254, 18
	s_lshl_b32 s3, s3, 1
	s_add_i32 s2, s2, s3
	v_and_b32_e32 v131, 0x30, v209
	v_lshl_add_u32 v131, v130, 13, v131
	v_add_u32_e32 v131, s2, v131
	v_xor_b32_e32 v134, 16, v209
	v_xor_b32_e32 v135, 32, v209
	v_lshlrev_b32_e32 v134, 2, v134
	v_lshlrev_b32_e32 v135, 2, v135
	s_waitcnt vmcnt(0)
	v_add_f32_e32 v212, v212, v213
	v_add_f32_e32 v214, v214, v215
	v_add_f32_e32 v216, v216, v217
	v_add_f32_e32 v218, v218, v219
	v_add_f32_e32 v220, v220, v221
	v_add_f32_e32 v222, v222, v223
	v_add_f32_e32 v224, v224, v225
	v_add_f32_e32 v226, v226, v227
	v_add_f32_e32 v228, v228, v229
	v_add_f32_e32 v230, v230, v231
	v_add_f32_e32 v232, v232, v233
	v_add_f32_e32 v234, v234, v235
	v_add_f32_e32 v236, v236, v237
	v_add_f32_e32 v238, v238, v239
	v_add_f32_e32 v240, v240, v241
	v_add_f32_e32 v242, v242, v243
	v_add_f32_e32 v212, v212, v214
	v_add_f32_e32 v216, v216, v218
	v_add_f32_e32 v220, v220, v222
	v_add_f32_e32 v224, v224, v226
	v_add_f32_e32 v228, v228, v230
	v_add_f32_e32 v232, v232, v234
	v_add_f32_e32 v236, v236, v238
	v_add_f32_e32 v240, v240, v242
	s_nop 0
	ds_bpermute_b32 v188, v134, v212
	ds_bpermute_b32 v189, v134, v216
	ds_bpermute_b32 v190, v134, v220
	ds_bpermute_b32 v191, v134, v224
	ds_bpermute_b32 v192, v134, v228
	ds_bpermute_b32 v193, v134, v232
	ds_bpermute_b32 v194, v134, v236
	ds_bpermute_b32 v195, v134, v240
	s_waitcnt lgkmcnt(0)
	v_add_f32_e32 v212, v212, v188
	v_add_f32_e32 v216, v216, v189
	v_add_f32_e32 v220, v220, v190
	v_add_f32_e32 v224, v224, v191
	v_add_f32_e32 v228, v228, v192
	v_add_f32_e32 v232, v232, v193
	v_add_f32_e32 v236, v236, v194
	v_add_f32_e32 v240, v240, v195
	s_nop 0
	ds_bpermute_b32 v188, v135, v212
	ds_bpermute_b32 v189, v135, v216
	ds_bpermute_b32 v190, v135, v220
	ds_bpermute_b32 v191, v135, v224
	ds_bpermute_b32 v192, v135, v228
	ds_bpermute_b32 v193, v135, v232
	ds_bpermute_b32 v194, v135, v236
	ds_bpermute_b32 v195, v135, v240
	s_waitcnt lgkmcnt(0)
	v_add_f32_e32 v212, v212, v188
	v_add_f32_e32 v216, v216, v189
	v_add_f32_e32 v220, v220, v190
	v_add_f32_e32 v224, v224, v191
	v_add_f32_e32 v228, v228, v192
	v_add_f32_e32 v232, v232, v193
	v_add_f32_e32 v236, v236, v194
	v_add_f32_e32 v240, v240, v195
	v_fmamk_f32 v212, v212, 0x3a800000, v207
	v_fmamk_f32 v216, v216, 0x3a800000, v207
	v_fmamk_f32 v220, v220, 0x3a800000, v207
	v_fmamk_f32 v224, v224, 0x3a800000, v207
	v_fmamk_f32 v228, v228, 0x3a800000, v207
	v_fmamk_f32 v232, v232, 0x3a800000, v207
	v_fmamk_f32 v236, v236, 0x3a800000, v207
	v_fmamk_f32 v240, v240, 0x3a800000, v207
	v_rsq_f32_e32 v160, v212
	v_rsq_f32_e32 v161, v216
	v_rsq_f32_e32 v162, v220
	v_rsq_f32_e32 v163, v224
	v_rsq_f32_e32 v164, v228
	v_rsq_f32_e32 v165, v232
	v_rsq_f32_e32 v166, v236
	v_rsq_f32_e32 v167, v240
	s_nop 0
	v_mul_f32_e32 v126, v126, v160
	v_mul_f32_e32 v127, v127, v160
	v_mul_f32_e32 v128, v128, v160
	v_mul_f32_e32 v129, v129, v160
	v_mul_f32_e32 v122, v122, v160
	v_mul_f32_e32 v123, v123, v160
	v_mul_f32_e32 v124, v124, v160
	v_mul_f32_e32 v125, v125, v160
	v_mul_f32_e32 v118, v118, v160
	v_mul_f32_e32 v119, v119, v160
	v_mul_f32_e32 v120, v120, v160
	v_mul_f32_e32 v121, v121, v160
	v_mul_f32_e32 v110, v110, v160
	v_mul_f32_e32 v111, v111, v160
	v_mul_f32_e32 v112, v112, v160
	v_mul_f32_e32 v113, v113, v160
	v_max_f32_e32 v126, 0, v126
	v_max_f32_e32 v127, 0, v127
	v_max_f32_e32 v128, 0, v128
	v_max_f32_e32 v129, 0, v129
	v_max_f32_e32 v122, 0, v122
	v_max_f32_e32 v123, 0, v123
	v_max_f32_e32 v124, 0, v124
	v_max_f32_e32 v125, 0, v125
	v_max_f32_e32 v118, 0, v118
	v_max_f32_e32 v119, 0, v119
	v_max_f32_e32 v120, 0, v120
	v_max_f32_e32 v121, 0, v121
	v_max_f32_e32 v110, 0, v110
	v_max_f32_e32 v111, 0, v111
	v_max_f32_e32 v112, 0, v112
	v_max_f32_e32 v113, 0, v113
	v_pk_mul_f32 v[126:127], v[126:127], v[126:127]
	v_pk_mul_f32 v[128:129], v[128:129], v[128:129]
	v_pk_mul_f32 v[122:123], v[122:123], v[122:123]
	v_pk_mul_f32 v[124:125], v[124:125], v[124:125]
	v_pk_mul_f32 v[118:119], v[118:119], v[118:119]
	v_pk_mul_f32 v[120:121], v[120:121], v[120:121]
	v_pk_mul_f32 v[110:111], v[110:111], v[110:111]
	v_pk_mul_f32 v[112:113], v[112:113], v[112:113]
	v_cvt_pk_bf16_f32 v126, v126, v127
	v_cvt_pk_bf16_f32 v127, v128, v129
	v_cvt_pk_bf16_f32 v128, v122, v123
	v_cvt_pk_bf16_f32 v129, v124, v125
	v_cvt_pk_bf16_f32 v118, v118, v119
	v_cvt_pk_bf16_f32 v119, v120, v121
	v_cvt_pk_bf16_f32 v120, v110, v111
	v_cvt_pk_bf16_f32 v121, v112, v113
	s_add_u32 s16, s0, 0x0
	s_addc_u32 s17, s1, 0
	global_store_dwordx4 v131, v[126:129], s[16:17] nt
	global_store_dwordx4 v131, v[118:121], s[16:17] offset:256 nt
	v_mul_f32_e32 v114, v114, v161
	v_mul_f32_e32 v115, v115, v161
	v_mul_f32_e32 v116, v116, v161
	v_mul_f32_e32 v117, v117, v161
	v_mul_f32_e32 v106, v106, v161
	v_mul_f32_e32 v107, v107, v161
	v_mul_f32_e32 v108, v108, v161
	v_mul_f32_e32 v109, v109, v161
	v_mul_f32_e32 v102, v102, v161
	v_mul_f32_e32 v103, v103, v161
	v_mul_f32_e32 v104, v104, v161
	v_mul_f32_e32 v105, v105, v161
	v_mul_f32_e32 v94, v94, v161
	v_mul_f32_e32 v95, v95, v161
	v_mul_f32_e32 v96, v96, v161
	v_mul_f32_e32 v97, v97, v161
	v_max_f32_e32 v114, 0, v114
	v_max_f32_e32 v115, 0, v115
	v_max_f32_e32 v116, 0, v116
	v_max_f32_e32 v117, 0, v117
	v_max_f32_e32 v106, 0, v106
	v_max_f32_e32 v107, 0, v107
	v_max_f32_e32 v108, 0, v108
	v_max_f32_e32 v109, 0, v109
	v_max_f32_e32 v102, 0, v102
	v_max_f32_e32 v103, 0, v103
	v_max_f32_e32 v104, 0, v104
	v_max_f32_e32 v105, 0, v105
	v_max_f32_e32 v94, 0, v94
	v_max_f32_e32 v95, 0, v95
	v_max_f32_e32 v96, 0, v96
	v_max_f32_e32 v97, 0, v97
	v_pk_mul_f32 v[114:115], v[114:115], v[114:115]
	v_pk_mul_f32 v[116:117], v[116:117], v[116:117]
	v_pk_mul_f32 v[106:107], v[106:107], v[106:107]
	v_pk_mul_f32 v[108:109], v[108:109], v[108:109]
	v_pk_mul_f32 v[102:103], v[102:103], v[102:103]
	v_pk_mul_f32 v[104:105], v[104:105], v[104:105]
	v_pk_mul_f32 v[94:95], v[94:95], v[94:95]
	v_pk_mul_f32 v[96:97], v[96:97], v[96:97]
	v_cvt_pk_bf16_f32 v114, v114, v115
	v_cvt_pk_bf16_f32 v115, v116, v117
	v_cvt_pk_bf16_f32 v116, v106, v107
	v_cvt_pk_bf16_f32 v117, v108, v109
	v_cvt_pk_bf16_f32 v102, v102, v103
	v_cvt_pk_bf16_f32 v103, v104, v105
	v_cvt_pk_bf16_f32 v104, v94, v95
	v_cvt_pk_bf16_f32 v105, v96, v97
	s_add_u32 s16, s0, 0x20000
	s_addc_u32 s17, s1, 0
	global_store_dwordx4 v131, v[114:117], s[16:17] nt
	global_store_dwordx4 v131, v[102:105], s[16:17] offset:256 nt
	v_mul_f32_e32 v98, v98, v162
	v_mul_f32_e32 v99, v99, v162
	v_mul_f32_e32 v100, v100, v162
	v_mul_f32_e32 v101, v101, v162
	v_mul_f32_e32 v90, v90, v162
	v_mul_f32_e32 v91, v91, v162
	v_mul_f32_e32 v92, v92, v162
	v_mul_f32_e32 v93, v93, v162
	v_mul_f32_e32 v86, v86, v162
	v_mul_f32_e32 v87, v87, v162
	v_mul_f32_e32 v88, v88, v162
	v_mul_f32_e32 v89, v89, v162
	v_mul_f32_e32 v78, v78, v162
	v_mul_f32_e32 v79, v79, v162
	v_mul_f32_e32 v80, v80, v162
	v_mul_f32_e32 v81, v81, v162
	v_max_f32_e32 v98, 0, v98
	v_max_f32_e32 v99, 0, v99
	v_max_f32_e32 v100, 0, v100
	v_max_f32_e32 v101, 0, v101
	v_max_f32_e32 v90, 0, v90
	v_max_f32_e32 v91, 0, v91
	v_max_f32_e32 v92, 0, v92
	v_max_f32_e32 v93, 0, v93
	v_max_f32_e32 v86, 0, v86
	v_max_f32_e32 v87, 0, v87
	v_max_f32_e32 v88, 0, v88
	v_max_f32_e32 v89, 0, v89
	v_max_f32_e32 v78, 0, v78
	v_max_f32_e32 v79, 0, v79
	v_max_f32_e32 v80, 0, v80
	v_max_f32_e32 v81, 0, v81
	v_pk_mul_f32 v[98:99], v[98:99], v[98:99]
	v_pk_mul_f32 v[100:101], v[100:101], v[100:101]
	v_pk_mul_f32 v[90:91], v[90:91], v[90:91]
	v_pk_mul_f32 v[92:93], v[92:93], v[92:93]
	v_pk_mul_f32 v[86:87], v[86:87], v[86:87]
	v_pk_mul_f32 v[88:89], v[88:89], v[88:89]
	v_pk_mul_f32 v[78:79], v[78:79], v[78:79]
	v_pk_mul_f32 v[80:81], v[80:81], v[80:81]
	v_cvt_pk_bf16_f32 v98, v98, v99
	v_cvt_pk_bf16_f32 v99, v100, v101
	v_cvt_pk_bf16_f32 v100, v90, v91
	v_cvt_pk_bf16_f32 v101, v92, v93
	v_cvt_pk_bf16_f32 v86, v86, v87
	v_cvt_pk_bf16_f32 v87, v88, v89
	v_cvt_pk_bf16_f32 v88, v78, v79
	v_cvt_pk_bf16_f32 v89, v80, v81
	s_add_u32 s16, s0, 0x40000
	s_addc_u32 s17, s1, 0
	global_store_dwordx4 v131, v[98:101], s[16:17] nt
	global_store_dwordx4 v131, v[86:89], s[16:17] offset:256 nt
	v_mul_f32_e32 v82, v82, v163
	v_mul_f32_e32 v83, v83, v163
	v_mul_f32_e32 v84, v84, v163
	v_mul_f32_e32 v85, v85, v163
	v_mul_f32_e32 v74, v74, v163
	v_mul_f32_e32 v75, v75, v163
	v_mul_f32_e32 v76, v76, v163
	v_mul_f32_e32 v77, v77, v163
	v_mul_f32_e32 v70, v70, v163
	v_mul_f32_e32 v71, v71, v163
	v_mul_f32_e32 v72, v72, v163
	v_mul_f32_e32 v73, v73, v163
	v_mul_f32_e32 v66, v66, v163
	v_mul_f32_e32 v67, v67, v163
	v_mul_f32_e32 v68, v68, v163
	v_mul_f32_e32 v69, v69, v163
	v_max_f32_e32 v82, 0, v82
	v_max_f32_e32 v83, 0, v83
	v_max_f32_e32 v84, 0, v84
	v_max_f32_e32 v85, 0, v85
	v_max_f32_e32 v74, 0, v74
	v_max_f32_e32 v75, 0, v75
	v_max_f32_e32 v76, 0, v76
	v_max_f32_e32 v77, 0, v77
	v_max_f32_e32 v70, 0, v70
	v_max_f32_e32 v71, 0, v71
	v_max_f32_e32 v72, 0, v72
	v_max_f32_e32 v73, 0, v73
	v_max_f32_e32 v66, 0, v66
	v_max_f32_e32 v67, 0, v67
	v_max_f32_e32 v68, 0, v68
	v_max_f32_e32 v69, 0, v69
	v_pk_mul_f32 v[82:83], v[82:83], v[82:83]
	v_pk_mul_f32 v[84:85], v[84:85], v[84:85]
	v_pk_mul_f32 v[74:75], v[74:75], v[74:75]
	v_pk_mul_f32 v[76:77], v[76:77], v[76:77]
	v_pk_mul_f32 v[70:71], v[70:71], v[70:71]
	v_pk_mul_f32 v[72:73], v[72:73], v[72:73]
	v_pk_mul_f32 v[66:67], v[66:67], v[66:67]
	v_pk_mul_f32 v[68:69], v[68:69], v[68:69]
	v_cvt_pk_bf16_f32 v82, v82, v83
	v_cvt_pk_bf16_f32 v83, v84, v85
	v_cvt_pk_bf16_f32 v84, v74, v75
	v_cvt_pk_bf16_f32 v85, v76, v77
	v_cvt_pk_bf16_f32 v70, v70, v71
	v_cvt_pk_bf16_f32 v71, v72, v73
	v_cvt_pk_bf16_f32 v72, v66, v67
	v_cvt_pk_bf16_f32 v73, v68, v69
	s_add_u32 s16, s0, 0x60000
	s_addc_u32 s17, s1, 0
	global_store_dwordx4 v131, v[82:85], s[16:17] nt
	global_store_dwordx4 v131, v[70:73], s[16:17] offset:256 nt
	v_mul_f32_e32 v62, v62, v164
	v_mul_f32_e32 v63, v63, v164
	v_mul_f32_e32 v64, v64, v164
	v_mul_f32_e32 v65, v65, v164
	v_mul_f32_e32 v58, v58, v164
	v_mul_f32_e32 v59, v59, v164
	v_mul_f32_e32 v60, v60, v164
	v_mul_f32_e32 v61, v61, v164
	v_mul_f32_e32 v54, v54, v164
	v_mul_f32_e32 v55, v55, v164
	v_mul_f32_e32 v56, v56, v164
	v_mul_f32_e32 v57, v57, v164
	v_mul_f32_e32 v46, v46, v164
	v_mul_f32_e32 v47, v47, v164
	v_mul_f32_e32 v48, v48, v164
	v_mul_f32_e32 v49, v49, v164
	v_max_f32_e32 v62, 0, v62
	v_max_f32_e32 v63, 0, v63
	v_max_f32_e32 v64, 0, v64
	v_max_f32_e32 v65, 0, v65
	v_max_f32_e32 v58, 0, v58
	v_max_f32_e32 v59, 0, v59
	v_max_f32_e32 v60, 0, v60
	v_max_f32_e32 v61, 0, v61
	v_max_f32_e32 v54, 0, v54
	v_max_f32_e32 v55, 0, v55
	v_max_f32_e32 v56, 0, v56
	v_max_f32_e32 v57, 0, v57
	v_max_f32_e32 v46, 0, v46
	v_max_f32_e32 v47, 0, v47
	v_max_f32_e32 v48, 0, v48
	v_max_f32_e32 v49, 0, v49
	v_pk_mul_f32 v[62:63], v[62:63], v[62:63]
	v_pk_mul_f32 v[64:65], v[64:65], v[64:65]
	v_pk_mul_f32 v[58:59], v[58:59], v[58:59]
	v_pk_mul_f32 v[60:61], v[60:61], v[60:61]
	v_pk_mul_f32 v[54:55], v[54:55], v[54:55]
	v_pk_mul_f32 v[56:57], v[56:57], v[56:57]
	v_pk_mul_f32 v[46:47], v[46:47], v[46:47]
	v_pk_mul_f32 v[48:49], v[48:49], v[48:49]
	v_cvt_pk_bf16_f32 v62, v62, v63
	v_cvt_pk_bf16_f32 v63, v64, v65
	v_cvt_pk_bf16_f32 v64, v58, v59
	v_cvt_pk_bf16_f32 v65, v60, v61
	v_cvt_pk_bf16_f32 v54, v54, v55
	v_cvt_pk_bf16_f32 v55, v56, v57
	v_cvt_pk_bf16_f32 v56, v46, v47
	v_cvt_pk_bf16_f32 v57, v48, v49
	s_add_u32 s16, s0, 0x100000
	s_addc_u32 s17, s1, 0
	global_store_dwordx4 v131, v[62:65], s[16:17] nt
	global_store_dwordx4 v131, v[54:57], s[16:17] offset:256 nt
	v_mul_f32_e32 v50, v50, v165
	v_mul_f32_e32 v51, v51, v165
	v_mul_f32_e32 v52, v52, v165
	v_mul_f32_e32 v53, v53, v165
	v_mul_f32_e32 v42, v42, v165
	v_mul_f32_e32 v43, v43, v165
	v_mul_f32_e32 v44, v44, v165
	v_mul_f32_e32 v45, v45, v165
	v_mul_f32_e32 v38, v38, v165
	v_mul_f32_e32 v39, v39, v165
	v_mul_f32_e32 v40, v40, v165
	v_mul_f32_e32 v41, v41, v165
	v_mul_f32_e32 v30, v30, v165
	v_mul_f32_e32 v31, v31, v165
	v_mul_f32_e32 v32, v32, v165
	v_mul_f32_e32 v33, v33, v165
	v_max_f32_e32 v50, 0, v50
	v_max_f32_e32 v51, 0, v51
	v_max_f32_e32 v52, 0, v52
	v_max_f32_e32 v53, 0, v53
	v_max_f32_e32 v42, 0, v42
	v_max_f32_e32 v43, 0, v43
	v_max_f32_e32 v44, 0, v44
	v_max_f32_e32 v45, 0, v45
	v_max_f32_e32 v38, 0, v38
	v_max_f32_e32 v39, 0, v39
	v_max_f32_e32 v40, 0, v40
	v_max_f32_e32 v41, 0, v41
	v_max_f32_e32 v30, 0, v30
	v_max_f32_e32 v31, 0, v31
	v_max_f32_e32 v32, 0, v32
	v_max_f32_e32 v33, 0, v33
	v_pk_mul_f32 v[50:51], v[50:51], v[50:51]
	v_pk_mul_f32 v[52:53], v[52:53], v[52:53]
	v_pk_mul_f32 v[42:43], v[42:43], v[42:43]
	v_pk_mul_f32 v[44:45], v[44:45], v[44:45]
	v_pk_mul_f32 v[38:39], v[38:39], v[38:39]
	v_pk_mul_f32 v[40:41], v[40:41], v[40:41]
	v_pk_mul_f32 v[30:31], v[30:31], v[30:31]
	v_pk_mul_f32 v[32:33], v[32:33], v[32:33]
	v_cvt_pk_bf16_f32 v50, v50, v51
	v_cvt_pk_bf16_f32 v51, v52, v53
	v_cvt_pk_bf16_f32 v52, v42, v43
	v_cvt_pk_bf16_f32 v53, v44, v45
	v_cvt_pk_bf16_f32 v38, v38, v39
	v_cvt_pk_bf16_f32 v39, v40, v41
	v_cvt_pk_bf16_f32 v40, v30, v31
	v_cvt_pk_bf16_f32 v41, v32, v33
	s_add_u32 s16, s0, 0x120000
	s_addc_u32 s17, s1, 0
	global_store_dwordx4 v131, v[50:53], s[16:17] nt
	global_store_dwordx4 v131, v[38:41], s[16:17] offset:256 nt
	v_mul_f32_e32 v34, v34, v166
	v_mul_f32_e32 v35, v35, v166
	v_mul_f32_e32 v36, v36, v166
	v_mul_f32_e32 v37, v37, v166
	v_mul_f32_e32 v26, v26, v166
	v_mul_f32_e32 v27, v27, v166
	v_mul_f32_e32 v28, v28, v166
	v_mul_f32_e32 v29, v29, v166
	v_mul_f32_e32 v22, v22, v166
	v_mul_f32_e32 v23, v23, v166
	v_mul_f32_e32 v24, v24, v166
	v_mul_f32_e32 v25, v25, v166
	v_mul_f32_e32 v14, v14, v166
	v_mul_f32_e32 v15, v15, v166
	v_mul_f32_e32 v16, v16, v166
	v_mul_f32_e32 v17, v17, v166
	v_max_f32_e32 v34, 0, v34
	v_max_f32_e32 v35, 0, v35
	v_max_f32_e32 v36, 0, v36
	v_max_f32_e32 v37, 0, v37
	v_max_f32_e32 v26, 0, v26
	v_max_f32_e32 v27, 0, v27
	v_max_f32_e32 v28, 0, v28
	v_max_f32_e32 v29, 0, v29
	v_max_f32_e32 v22, 0, v22
	v_max_f32_e32 v23, 0, v23
	v_max_f32_e32 v24, 0, v24
	v_max_f32_e32 v25, 0, v25
	v_max_f32_e32 v14, 0, v14
	v_max_f32_e32 v15, 0, v15
	v_max_f32_e32 v16, 0, v16
	v_max_f32_e32 v17, 0, v17
	v_pk_mul_f32 v[34:35], v[34:35], v[34:35]
	v_pk_mul_f32 v[36:37], v[36:37], v[36:37]
	v_pk_mul_f32 v[26:27], v[26:27], v[26:27]
	v_pk_mul_f32 v[28:29], v[28:29], v[28:29]
	v_pk_mul_f32 v[22:23], v[22:23], v[22:23]
	v_pk_mul_f32 v[24:25], v[24:25], v[24:25]
	v_pk_mul_f32 v[14:15], v[14:15], v[14:15]
	v_pk_mul_f32 v[16:17], v[16:17], v[16:17]
	v_cvt_pk_bf16_f32 v34, v34, v35
	v_cvt_pk_bf16_f32 v35, v36, v37
	v_cvt_pk_bf16_f32 v36, v26, v27
	v_cvt_pk_bf16_f32 v37, v28, v29
	v_cvt_pk_bf16_f32 v22, v22, v23
	v_cvt_pk_bf16_f32 v23, v24, v25
	v_cvt_pk_bf16_f32 v24, v14, v15
	v_cvt_pk_bf16_f32 v25, v16, v17
	s_add_u32 s16, s0, 0x140000
	s_addc_u32 s17, s1, 0
	global_store_dwordx4 v131, v[34:37], s[16:17] nt
	global_store_dwordx4 v131, v[22:25], s[16:17] offset:256 nt
	v_mul_f32_e32 v18, v18, v167
	v_mul_f32_e32 v19, v19, v167
	v_mul_f32_e32 v20, v20, v167
	v_mul_f32_e32 v21, v21, v167
	v_mul_f32_e32 v10, v10, v167
	v_mul_f32_e32 v11, v11, v167
	v_mul_f32_e32 v12, v12, v167
	v_mul_f32_e32 v13, v13, v167
	v_mul_f32_e32 v6, v6, v167
	v_mul_f32_e32 v7, v7, v167
	v_mul_f32_e32 v8, v8, v167
	v_mul_f32_e32 v9, v9, v167
	v_mul_f32_e32 v2, v2, v167
	v_mul_f32_e32 v3, v3, v167
	v_mul_f32_e32 v4, v4, v167
	v_mul_f32_e32 v5, v5, v167
	v_max_f32_e32 v18, 0, v18
	v_max_f32_e32 v19, 0, v19
	v_max_f32_e32 v20, 0, v20
	v_max_f32_e32 v21, 0, v21
	v_max_f32_e32 v10, 0, v10
	v_max_f32_e32 v11, 0, v11
	v_max_f32_e32 v12, 0, v12
	v_max_f32_e32 v13, 0, v13
	v_max_f32_e32 v6, 0, v6
	v_max_f32_e32 v7, 0, v7
	v_max_f32_e32 v8, 0, v8
	v_max_f32_e32 v9, 0, v9
	v_max_f32_e32 v2, 0, v2
	v_max_f32_e32 v3, 0, v3
	v_max_f32_e32 v4, 0, v4
	v_max_f32_e32 v5, 0, v5
	v_pk_mul_f32 v[18:19], v[18:19], v[18:19]
	v_pk_mul_f32 v[20:21], v[20:21], v[20:21]
	v_pk_mul_f32 v[10:11], v[10:11], v[10:11]
	v_pk_mul_f32 v[12:13], v[12:13], v[12:13]
	v_pk_mul_f32 v[6:7], v[6:7], v[6:7]
	v_pk_mul_f32 v[8:9], v[8:9], v[8:9]
	v_pk_mul_f32 v[2:3], v[2:3], v[2:3]
	v_pk_mul_f32 v[4:5], v[4:5], v[4:5]
	v_cvt_pk_bf16_f32 v18, v18, v19
	v_cvt_pk_bf16_f32 v19, v20, v21
	v_cvt_pk_bf16_f32 v20, v10, v11
	v_cvt_pk_bf16_f32 v21, v12, v13
	v_cvt_pk_bf16_f32 v6, v6, v7
	v_cvt_pk_bf16_f32 v7, v8, v9
	v_cvt_pk_bf16_f32 v8, v2, v3
	v_cvt_pk_bf16_f32 v9, v4, v5
	s_add_u32 s16, s0, 0x160000
	s_addc_u32 s17, s1, 0
	global_store_dwordx4 v131, v[18:21], s[16:17] nt
	global_store_dwordx4 v131, v[6:9], s[16:17] offset:256 nt
	s_mov_b64 s[2:3], -1
	s_andn2_b64 vcc, exec, s[4:5]
	s_cbranch_vccnz .LBB0_945
	s_and_b64 vcc, exec, s[40:41]
	s_cbranch_vccnz .LBB0_944
	s_barrier
	s_branch .LBB0_944
